# v048 + GEMM phase prologues issue all fourteen staging loads of K-tiles 0 and 1 before the first wait (vmcnt(8)); five redundant post-barrier compiler waits dropped
# speedup vs baseline: 1.0085x; 1.0027x over previous
; #define PG8_STAGE(bufoff, gbase, voff) do { _Pragma("unroll") for (int _i = 0; _i < 2; ++_i) \
;         __builtin_amdgcn_global_load_lds((const unsigned*)((const char*)(gbase) + (voff)[_i]), (PG8_LAS unsigned*)(lds + (bufoff) + ldsw + _i * 8192), 16, 0, 0); } while (0)
; #define PG8_WAIT_V(n) asm volatile("s_waitcnt vmcnt(" #n ")" ::: "memory")
; #define PG8_BAR __builtin_amdgcn_s_barrier()
; template <class Epi, class Sched, bool ALIGN_EPI = false, bool SP2 = false, bool PAIR_ACC = false>
; __device__ __forceinline__ void gemm_phase(PG8_LAS unsigned char* lds, const Gemm g, const Sched& S, const Epi& E) {
;     ...
;         PG8_STAGE(PG8_SB(0, 0), cB, voffB); PG8_STAGE(PG8_SB(0, 1), cB + hstep, voffB); PG8_STAGE(PG8_SA(0, 0), cA, voffA); PG8_STAGE(PG8_SA(0, 1), cA + hstep, voffA);
;         if (wr == 1) PG8_BAR;
;         PG8_WAIT_V(2); PG8_BAR;
;         PG8_STAGE(PG8_SB(1, 0), cB + kstep, voffB); PG8_STAGE(PG8_SA(1, 0), cA + kstep, voffA); PG8_STAGE(PG8_SB(1, 1), cB + hstep + kstep, voffB);
;         PG8_WAIT_V(6); PG8_BAR;
;     __device__ __forceinline__ void operator()(const f32x4 (&acc)[2][2][4][2], const Unit& u, int wr, int wc, int fr, int fq) const {
;     ...
;         const bool ropelane = ((wc & 1) == 0) && (fq < 2);
;         const float sgn = (fq == 0) ? -1.f : 1.f;
.LBB0_175:
	s_add_u32 s44, s28, 0x100000
	s_addc_u32 s45, s29, 0
	s_add_u32 s48, s28, 0xf400000
	s_mov_b64 s[50:51], 0x80
	s_addc_u32 s49, s29, 0
	s_and_b32 s9, s4, 3
	s_add_i32 m0, s69, 0x18000
	v_lshl_add_u64 v[8:9], v[8:9], 0, s[50:51]
	s_lshl_b32 s6, s5, 13
	s_lshl_b32 s7, s9, 12
	global_load_lds_dwordx4 v[8:9], off
	v_lshl_add_u64 v[6:7], v[6:7], 0, s[50:51]
	s_add_i32 m0, s69, 0x1a000
	s_add_i32 s37, s69, 0x8000
	s_add_i32 s75, s69, 0xa000
	v_and_b32_e32 v17, 15, v10
	global_load_lds_dwordx4 v[6:7], off
	v_lshl_add_u64 v[2:3], v[2:3], 0, s[50:51]
	s_mov_b32 m0, s37
	s_add_u32 s4, s14, 0x40080
	v_lshl_or_b32 v157, s5, 6, v17
	global_load_lds_dwordx4 v[2:3], off
	v_lshl_add_u64 v[2:3], v[4:5], 0, s[50:51]
	s_mov_b32 m0, s75
	s_addc_u32 s5, s15, 0
	global_load_lds_dwordx4 v[2:3], off
	s_add_i32 m0, s69, 0x1c000
	v_lshl_add_u64 v[2:3], s[4:5], 0, v[148:149]
	global_load_lds_dwordx4 v[2:3], off
	v_lshl_add_u64 v[2:3], s[4:5], 0, v[152:153]
	s_add_i32 m0, s69, 0x1e000
	v_bfe_u32 v18, v10, 4, 2
	global_load_lds_dwordx4 v[2:3], off
	s_waitcnt vmcnt(8)
	s_barrier
	v_lshlrev_b32_e32 v19, 3, v18
	s_cmpk_lt_u32 s8, 0x100
	v_lshlrev_b32_e32 v20, 4, v18
	v_lshlrev_b32_e32 v3, 2, v10
	s_cselect_b64 s[52:53], -1, 0
	v_lshl_or_b32 v156, s9, 5, v19
	s_bitcmp0_b32 s8, 6
	v_lshl_or_b32 v2, v17, 6, v20
	v_and_b32_e32 v3, 32, v3
	s_cselect_b64 s[54:55], -1, 0
	s_lshl_b32 s8, s9, 1
	v_lshlrev_b32_e32 v154, 1, v156
	v_bitop3_b32 v4, v2, s6, v3 bitop3:0xde
	v_bitop3_b32 v173, v2, s7, v3 bitop3:0xde
	s_or_b32 s46, s8, 0xffffffb8
	v_lshl_add_u64 v[2:3], s[28:29], 0, v[154:155]
	s_mov_b64 s[8:9], 0xd300000
	v_lshl_add_u64 v[162:163], v[2:3], 0, s[8:9]
	s_mov_b64 s[8:9], 0x6b00000
	v_lshl_add_u64 v[164:165], v[2:3], 0, s[8:9]
	s_ashr_i32 s47, s3, 31
	s_ashr_i32 s24, s2, 31
	s_ashr_i32 s8, s2, 3
	s_cmp_gt_i32 s8, 7
	s_cselect_b64 s[56:57], -1, 0
	s_add_i32 s9, s8, -8
	v_writelane_b32 v246, s9, 14
	s_and_b32 s13, s8, 7
	v_readlane_b32 s9, v246, 2
	s_and_b32 s9, s9, 56
	s_or_b32 s13, s9, s13
	v_writelane_b32 v246, s13, 16
	s_add_i32 s8, s9, s8
	v_writelane_b32 v246, s8, 18
	s_mov_b64 s[8:9], 0x8b00000
	v_lshl_add_u64 v[166:167], v[2:3], 0, s[8:9]
	s_mov_b64 s[8:9], 0x8f00000
	v_lshl_add_u64 v[168:169], v[2:3], 0, s[8:9]
	v_lshlrev_b32_e32 v2, 14, v11
	v_and_b32_e32 v2, 0xffff8000, v2
	v_lshl_add_u32 v2, v12, 11, v2
	v_and_b32_e32 v3, 1, v11
	v_lshl_or_b32 v2, v3, 6, v2
	v_lshl_add_u32 v170, v13, 1, v2
	v_lshlrev_b32_e32 v2, 14, v14
	v_and_b32_e32 v2, 0xffff8000, v2
	v_lshl_add_u32 v2, v15, 11, v2
	v_and_b32_e32 v3, 1, v14
	v_readlane_b32 s8, v246, 8
	s_waitcnt vmcnt(6)
	v_cmp_eq_u32_e64 s[6:7], 0, v18
	v_lshl_or_b32 v2, v3, 6, v2
	v_readlane_b32 s9, v246, 9
	v_cndmask_b32_e64 v158, 1.0, -1.0, s[6:7]
	v_lshl_add_u32 v174, v16, 1, v2
	v_cndmask_b32_e64 v2, 0, 1, s[8:9]
	s_add_i32 s25, 0, 0x10000
	s_add_i32 s35, 0, 0x14000
	v_cmp_gt_u32_e64 s[4:5], 2, v18
	v_mov_b32_e32 v159, v158
	v_mov_b32_e32 v160, v158
	v_mov_b32_e32 v161, v158
	v_mov_b32_e32 v171, v155
	v_mov_b32_e32 v175, v155
	v_cmp_ne_u32_e64 s[8:9], 1, v2
	s_mov_b64 s[58:59], 0x100
	v_add_u32_e32 v196, s25, v173
	v_add_u32_e32 v197, s35, v173
	v_add_u32_e32 v198, 0, v4
	s_mov_b32 s60, 0xbfb8aa3b
	s_mov_b32 s62, 0x3e6d3388
	s_mov_b32 s64, 0x3f07dc22
	s_mov_b32 s66, 0xbf3a00e3
	s_mov_b32 s68, 0x3f35f0e3
	s_mov_b32 s70, 0xbe11a98e
	s_mov_b32 s72, 0x3e027906
	s_mov_b32 s74, 0xbf38aa3b
	s_mov_b32 s76, 0x3e38aa3b
	v_mov_b64_e32 v[176:177], 0x53f
	v_mbcnt_hi_u32_b32 v199, -1, v1
	s_mov_b32 s13, 0
	s_barrier
	s_branch .LBB0_178

; #define PG8_STAGE(bufoff, gbase, voff) do { _Pragma("unroll") for (int _i = 0; _i < 2; ++_i) \
;         __builtin_amdgcn_global_load_lds((const unsigned*)((const char*)(gbase) + (voff)[_i]), (PG8_LAS unsigned*)(lds + (bufoff) + ldsw + _i * 8192), 16, 0, 0); } while (0)
; #define PG8_WAIT_V(n) asm volatile("s_waitcnt vmcnt(" #n ")" ::: "memory")
; #define PG8_BAR __builtin_amdgcn_s_barrier()
; template <class Epi, class Sched, bool ALIGN_EPI = false, bool SP2 = false, bool PAIR_ACC = false>
; __device__ __forceinline__ void gemm_phase(PG8_LAS unsigned char* lds, const Gemm g, const Sched& S, const Epi& E) {
;     ...
;     f32x4 acc[2][2][4][2];
; #pragma unroll
;     for (int a = 0; a < 2; ++a)
; #pragma unroll
;         for (int b = 0; b < 2; ++b)
; #pragma unroll
;             for (int m = 0; m < 4; ++m)
; #pragma unroll
;                 for (int n = 0; n < 2; ++n) acc[a][b][m][n] = (f32x4){0.f, 0.f, 0.f, 0.f};
;     ...
;         PG8_STAGE(PG8_SB(0, 0), cB, voffB); PG8_STAGE(PG8_SB(0, 1), cB + hstep, voffB); PG8_STAGE(PG8_SA(0, 0), cA, voffA); PG8_STAGE(PG8_SA(0, 1), cA + hstep, voffA);
;         if (wr == 1) PG8_BAR;
;         PG8_WAIT_V(2); PG8_BAR;
;         PG8_STAGE(PG8_SB(1, 0), cB + kstep, voffB); PG8_STAGE(PG8_SA(1, 0), cA + kstep, voffA); PG8_STAGE(PG8_SB(1, 1), cB + hstep + kstep, voffB);
;         PG8_WAIT_V(6); PG8_BAR;
.LBB0_573:
	s_add_u32 s12, s6, 0x2b00000
	s_addc_u32 s13, s7, 0
	s_add_u32 s14, s6, 0xb300000
	v_lshrrev_b32_e32 v18, 1, v10
	s_addc_u32 s15, s7, 0
	v_and_b32_e32 v18, 24, v18
	s_add_u32 s16, s6, 0xd300000
	v_and_b32_e32 v17, 15, v10
	v_lshlrev_b32_e32 v19, 1, v18
	v_lshlrev_b32_e32 v10, 2, v10
	s_addc_u32 s17, s7, 0
	v_lshl_or_b32 v173, s8, 6, v17
	v_lshl_or_b32 v17, v17, 6, v19
	s_lshl_b32 s6, s8, 13
	v_and_b32_e32 v10, 32, v10
	v_bitop3_b32 v19, v17, s6, v10 bitop3:0xde
	s_lshl_b32 s6, s9, 5
	s_mov_b64 s[18:19], 0x80
	s_and_b32 s8, s6, 0x60
	s_add_i32 m0, s34, 0x18000
	v_lshl_add_u64 v[8:9], v[8:9], 0, s[18:19]
	s_lshl_b32 s6, s8, 7
	global_load_lds_dwordx4 v[8:9], off
	v_lshl_add_u64 v[6:7], v[6:7], 0, s[18:19]
	s_add_i32 m0, s34, 0x1a000
	s_add_i32 s41, s34, 0x8000
	s_add_i32 s44, s34, 0xa000
	v_bitop3_b32 v206, v17, s6, v10 bitop3:0xde
	global_load_lds_dwordx4 v[6:7], off
	v_lshl_add_u64 v[2:3], v[2:3], 0, s[18:19]
	s_mov_b32 m0, s41
	s_add_u32 s6, s54, 0x40080
	global_load_lds_dwordx4 v[2:3], off
	v_lshl_add_u64 v[2:3], v[4:5], 0, s[18:19]
	s_mov_b32 m0, s44
	s_addc_u32 s7, s55, 0
	global_load_lds_dwordx4 v[2:3], off
	s_add_i32 m0, s34, 0x1c000
	v_lshl_add_u64 v[2:3], s[6:7], 0, v[160:161]
	global_load_lds_dwordx4 v[2:3], off
	v_lshl_add_u64 v[2:3], s[6:7], 0, v[164:165]
	s_add_i32 m0, s34, 0x1e000
	s_cmpk_lt_u32 s20, 0x100
	global_load_lds_dwordx4 v[2:3], off
	s_waitcnt vmcnt(8)
	s_barrier
	v_lshlrev_b32_e32 v2, 14, v11
	v_and_b32_e32 v2, 0xffff8000, v2
	v_lshl_add_u32 v2, v12, 11, v2
	v_and_b32_e32 v3, 1, v11
	v_lshl_or_b32 v2, v3, 6, v2
	v_lshl_add_u32 v168, v13, 1, v2
	v_lshlrev_b32_e32 v2, 14, v14
	v_and_b32_e32 v2, 0xffff8000, v2
	s_waitcnt vmcnt(6)
	v_lshl_add_u32 v2, v15, 11, v2
	v_and_b32_e32 v3, 1, v14
	v_lshl_or_b32 v2, v3, 6, v2
	s_cselect_b64 s[20:21], -1, 0
	s_ashr_i32 s45, s2, 31
	v_or_b32_e32 v207, s8, v18
	v_mov_b32_e32 v169, v167
	v_lshl_add_u32 v170, v16, 1, v2
	v_mov_b32_e32 v171, v167
	v_mov_b64_e32 v[174:175], 0x100
	v_mov_b64_e32 v[176:177], 0xff
	s_add_i32 s46, 0, 0x10000
	s_add_i32 s47, 0, 0x14000
	v_add_u32_e32 v208, 0, v19
	v_mov_b32_e32 v2, v167
	v_mov_b32_e32 v3, v167
	v_mov_b32_e32 v4, v167
	v_mov_b32_e32 v5, v167
	v_mov_b32_e32 v6, v167
	v_mov_b32_e32 v7, v167
	v_mov_b32_e32 v8, v167
	v_mov_b32_e32 v9, v167
	v_mov_b32_e32 v10, v167
	v_mov_b32_e32 v11, v167
	v_mov_b32_e32 v12, v167
	v_mov_b32_e32 v13, v167
	v_mov_b32_e32 v14, v167
	v_mov_b32_e32 v15, v167
	v_mov_b32_e32 v16, v167
	v_mov_b32_e32 v17, v167
	v_mov_b32_e32 v18, v167
	v_mov_b32_e32 v19, v167
	v_mov_b32_e32 v20, v167
	v_mov_b32_e32 v21, v167
	v_mov_b32_e32 v22, v167
	v_mov_b32_e32 v23, v167
	v_mov_b32_e32 v24, v167
	v_mov_b32_e32 v25, v167
	v_mov_b32_e32 v26, v167
	v_mov_b32_e32 v27, v167
	v_mov_b32_e32 v28, v167
	v_mov_b32_e32 v29, v167
	v_mov_b32_e32 v30, v167
	v_mov_b32_e32 v31, v167
	v_mov_b32_e32 v32, v167
	v_mov_b32_e32 v33, v167
	v_mov_b32_e32 v34, v167
	v_mov_b32_e32 v35, v167
	v_mov_b32_e32 v36, v167
	v_mov_b32_e32 v37, v167
	v_mov_b32_e32 v38, v167
	v_mov_b32_e32 v39, v167
	v_mov_b32_e32 v40, v167
	v_mov_b32_e32 v41, v167
	v_mov_b32_e32 v42, v167
	v_mov_b32_e32 v43, v167
	v_mov_b32_e32 v44, v167
	v_mov_b32_e32 v45, v167
	v_mov_b32_e32 v46, v167
	v_mov_b32_e32 v47, v167
	v_mov_b32_e32 v48, v167
	v_mov_b32_e32 v49, v167
	v_mov_b32_e32 v50, v167
	v_mov_b32_e32 v51, v167
	v_mov_b32_e32 v52, v167
	v_mov_b32_e32 v53, v167
	v_mov_b32_e32 v54, v167
	v_mov_b32_e32 v55, v167
	v_mov_b32_e32 v56, v167
	v_mov_b32_e32 v57, v167
	v_mov_b32_e32 v58, v167
	v_mov_b32_e32 v59, v167
	v_mov_b32_e32 v60, v167
	v_mov_b32_e32 v61, v167
	v_mov_b32_e32 v62, v167
	v_mov_b32_e32 v63, v167
	v_mov_b32_e32 v64, v167
	v_mov_b32_e32 v65, v167
	v_mov_b32_e32 v66, v167
	v_mov_b32_e32 v67, v167
	v_mov_b32_e32 v68, v167
	v_mov_b32_e32 v69, v167
	v_mov_b32_e32 v70, v167
	v_mov_b32_e32 v71, v167
	v_mov_b32_e32 v72, v167
	v_mov_b32_e32 v73, v167
	v_mov_b32_e32 v74, v167
	v_mov_b32_e32 v75, v167
	v_mov_b32_e32 v76, v167
	v_mov_b32_e32 v77, v167
	v_mov_b32_e32 v78, v167
	v_mov_b32_e32 v79, v167
	v_mov_b32_e32 v80, v167
	v_mov_b32_e32 v81, v167
	v_mov_b32_e32 v82, v167
	v_mov_b32_e32 v83, v167
	v_mov_b32_e32 v84, v167
	v_mov_b32_e32 v85, v167
	v_mov_b32_e32 v86, v167
	v_mov_b32_e32 v87, v167
	v_mov_b32_e32 v88, v167
	v_mov_b32_e32 v89, v167
	v_mov_b32_e32 v90, v167
	v_mov_b32_e32 v91, v167
	v_mov_b32_e32 v92, v167
	v_mov_b32_e32 v93, v167
	v_mov_b32_e32 v94, v167
	v_mov_b32_e32 v95, v167
	v_mov_b32_e32 v96, v167
	v_mov_b32_e32 v97, v167
	v_mov_b32_e32 v98, v167
	v_mov_b32_e32 v99, v167
	v_mov_b32_e32 v100, v167
	v_mov_b32_e32 v101, v167
	v_mov_b32_e32 v102, v167
	v_mov_b32_e32 v103, v167
	v_mov_b32_e32 v104, v167
	v_mov_b32_e32 v105, v167
	v_mov_b32_e32 v106, v167
	v_mov_b32_e32 v107, v167
	v_mov_b32_e32 v108, v167
	v_mov_b32_e32 v109, v167
	v_mov_b32_e32 v110, v167
	v_mov_b32_e32 v111, v167
	v_mov_b32_e32 v112, v167
	v_mov_b32_e32 v113, v167
	v_mov_b32_e32 v114, v167
	v_mov_b32_e32 v115, v167
	v_mov_b32_e32 v116, v167
	v_mov_b32_e32 v117, v167
	v_mov_b32_e32 v118, v167
	v_mov_b32_e32 v119, v167
	v_mov_b32_e32 v120, v167
	v_mov_b32_e32 v121, v167
	v_mov_b32_e32 v122, v167
	v_mov_b32_e32 v123, v167
	v_mov_b32_e32 v124, v167
	v_mov_b32_e32 v125, v167
	v_mov_b32_e32 v126, v167
	v_mov_b32_e32 v127, v167
	v_mov_b32_e32 v128, v167
	v_mov_b32_e32 v129, v167
	s_barrier
	s_branch .LBB0_576

; #define PG8_STAGE(bufoff, gbase, voff) do { _Pragma("unroll") for (int _i = 0; _i < 2; ++_i) \
;         __builtin_amdgcn_global_load_lds((const unsigned*)((const char*)(gbase) + (voff)[_i]), (PG8_LAS unsigned*)(lds + (bufoff) + ldsw + _i * 8192), 16, 0, 0); } while (0)
; #define PG8_WAIT_V(n) asm volatile("s_waitcnt vmcnt(" #n ")" ::: "memory")
; #define PG8_BAR __builtin_amdgcn_s_barrier()
; template <class Epi, class Sched, bool ALIGN_EPI = false, bool SP2 = false, bool PAIR_ACC = false>
; __device__ __forceinline__ void gemm_phase(PG8_LAS unsigned char* lds, const Gemm g, const Sched& S, const Epi& E) {
;     ...
;     f32x4 acc[2][2][4][2];
; #pragma unroll
;     for (int a = 0; a < 2; ++a)
; #pragma unroll
;         for (int b = 0; b < 2; ++b)
; #pragma unroll
;             for (int m = 0; m < 4; ++m)
; #pragma unroll
;                 for (int n = 0; n < 2; ++n) acc[a][b][m][n] = (f32x4){0.f, 0.f, 0.f, 0.f};
;     ...
;         PG8_STAGE(PG8_SB(0, 0), cB, voffB); PG8_STAGE(PG8_SB(0, 1), cB + hstep, voffB); PG8_STAGE(PG8_SA(0, 0), cA, voffA); PG8_STAGE(PG8_SA(0, 1), cA + hstep, voffA);
;         if (wr == 1) PG8_BAR;
;         PG8_WAIT_V(2); PG8_BAR;
;         PG8_STAGE(PG8_SB(1, 0), cB + kstep, voffB); PG8_STAGE(PG8_SA(1, 0), cA + kstep, voffA); PG8_STAGE(PG8_SB(1, 1), cB + hstep + kstep, voffB);
;         PG8_WAIT_V(6); PG8_BAR;
.LBB0_717:
	v_and_b32_e32 v171, 15, v166
	v_and_b32_e32 v16, 48, v166
	v_lshlrev_b32_e32 v17, 2, v166
	s_mov_b64 s[28:29], 0x80
	s_sext_i32_i8 s10, s6
	s_and_b32 s17, s11, 3
	s_lshl_b32 s6, s23, 13
	v_lshl_or_b32 v16, v171, 6, v16
	v_and_b32_e32 v17, 32, v17
	s_add_i32 m0, s40, 0x18000
	v_lshl_add_u64 v[8:9], v[8:9], 0, s[28:29]
	s_lshl_b32 s5, s23, 6
	v_bitop3_b32 v18, v16, s6, v17 bitop3:0xde
	s_lshl_b32 s6, s17, 12
	global_load_lds_dwordx4 v[8:9], off
	v_lshl_add_u64 v[6:7], v[6:7], 0, s[28:29]
	s_add_i32 m0, s40, 0x1a000
	s_add_i32 s47, s40, 0x8000
	s_add_i32 s56, s40, 0xa000
	global_load_lds_dwordx4 v[6:7], off
	v_lshl_add_u64 v[4:5], v[4:5], 0, s[28:29]
	s_mov_b32 m0, s47
	s_add_u32 s8, s52, 0x40080
	global_load_lds_dwordx4 v[4:5], off
	v_lshl_add_u64 v[2:3], v[2:3], 0, s[28:29]
	s_mov_b32 m0, s56
	s_addc_u32 s9, s53, 0
	global_load_lds_dwordx4 v[2:3], off
	s_add_i32 m0, s40, 0x1c000
	v_lshl_add_u64 v[2:3], s[8:9], 0, v[132:133]
	global_load_lds_dwordx4 v[2:3], off
	v_lshl_add_u64 v[2:3], s[8:9], 0, v[136:137]
	s_add_i32 m0, s40, 0x1e000
	v_bitop3_b32 v150, v16, s6, v17 bitop3:0xde
	global_load_lds_dwordx4 v[2:3], off
	s_waitcnt vmcnt(8)
	s_barrier
	v_lshlrev_b32_e32 v2, 14, v10
	v_and_b32_e32 v2, 0xffff8000, v2
	v_lshl_add_u32 v2, v11, 11, v2
	v_and_b32_e32 v3, 1, v10
	v_lshl_or_b32 v2, v3, 6, v2
	s_mov_b64 s[6:7], 0x40080
	v_lshl_add_u32 v2, v12, 1, v2
	v_mov_b32_e32 v3, v133
	v_lshl_add_u64 v[138:139], v[2:3], 0, s[6:7]
	v_lshlrev_b32_e32 v2, 14, v13
	v_and_b32_e32 v2, 0xffff8000, v2
	v_lshl_add_u32 v2, v14, 11, v2
	v_and_b32_e32 v3, 1, v13
	s_waitcnt vmcnt(6)
	v_lshl_or_b32 v2, v3, 6, v2
	v_lshl_add_u32 v2, v15, 1, v2
	v_mov_b32_e32 v3, v133
	v_or_b32_e32 v170, s5, v171
	v_lshl_add_u64 v[140:141], v[2:3], 0, s[6:7]
	v_mov_b64_e32 v[142:143], 0x100
	v_mov_b64_e32 v[144:145], 0xff
	s_add_i32 s57, 0, 0x10000
	s_add_i32 s58, 0, 0x14000
	v_add_u32_e32 v151, 0, v18
	v_mov_b32_e32 v2, v133
	v_mov_b32_e32 v4, v133
	v_mov_b32_e32 v5, v133
	v_mov_b32_e32 v6, v133
	v_mov_b32_e32 v7, v133
	v_mov_b32_e32 v8, v133
	v_mov_b32_e32 v9, v133
	v_mov_b32_e32 v18, v133
	v_mov_b32_e32 v19, v133
	v_mov_b32_e32 v20, v133
	v_mov_b32_e32 v21, v133
	v_mov_b32_e32 v22, v133
	v_mov_b32_e32 v23, v133
	v_mov_b32_e32 v24, v133
	v_mov_b32_e32 v25, v133
	v_mov_b32_e32 v34, v133
	v_mov_b32_e32 v35, v133
	v_mov_b32_e32 v36, v133
	v_mov_b32_e32 v37, v133
	v_mov_b32_e32 v38, v133
	v_mov_b32_e32 v39, v133
	v_mov_b32_e32 v40, v133
	v_mov_b32_e32 v41, v133
	v_mov_b32_e32 v42, v133
	v_mov_b32_e32 v43, v133
	v_mov_b32_e32 v44, v133
	v_mov_b32_e32 v45, v133
	v_mov_b32_e32 v46, v133
	v_mov_b32_e32 v47, v133
	v_mov_b32_e32 v48, v133
	v_mov_b32_e32 v49, v133
	v_mov_b32_e32 v10, v133
	v_mov_b32_e32 v11, v133
	v_mov_b32_e32 v12, v133
	v_mov_b32_e32 v13, v133
	v_mov_b32_e32 v14, v133
	v_mov_b32_e32 v15, v133
	v_mov_b32_e32 v16, v133
	v_mov_b32_e32 v17, v133
	v_mov_b32_e32 v26, v133
	v_mov_b32_e32 v27, v133
	v_mov_b32_e32 v28, v133
	v_mov_b32_e32 v29, v133
	v_mov_b32_e32 v30, v133
	v_mov_b32_e32 v31, v133
	v_mov_b32_e32 v32, v133
	v_mov_b32_e32 v33, v133
	v_mov_b32_e32 v74, v133
	v_mov_b32_e32 v75, v133
	v_mov_b32_e32 v76, v133
	v_mov_b32_e32 v77, v133
	v_mov_b32_e32 v78, v133
	v_mov_b32_e32 v79, v133
	v_mov_b32_e32 v80, v133
	v_mov_b32_e32 v81, v133
	v_mov_b32_e32 v82, v133
	v_mov_b32_e32 v83, v133
	v_mov_b32_e32 v84, v133
	v_mov_b32_e32 v85, v133
	v_mov_b32_e32 v86, v133
	v_mov_b32_e32 v87, v133
	v_mov_b32_e32 v88, v133
	v_mov_b32_e32 v89, v133
	v_mov_b32_e32 v50, v133
	v_mov_b32_e32 v51, v133
	v_mov_b32_e32 v52, v133
	v_mov_b32_e32 v53, v133
	v_mov_b32_e32 v54, v133
	v_mov_b32_e32 v55, v133
	v_mov_b32_e32 v56, v133
	v_mov_b32_e32 v57, v133
	v_mov_b32_e32 v58, v133
	v_mov_b32_e32 v59, v133
	v_mov_b32_e32 v60, v133
	v_mov_b32_e32 v61, v133
	v_mov_b32_e32 v62, v133
	v_mov_b32_e32 v63, v133
	v_mov_b32_e32 v64, v133
	v_mov_b32_e32 v65, v133
	v_mov_b32_e32 v66, v133
	v_mov_b32_e32 v67, v133
	v_mov_b32_e32 v68, v133
	v_mov_b32_e32 v69, v133
	v_mov_b32_e32 v70, v133
	v_mov_b32_e32 v71, v133
	v_mov_b32_e32 v72, v133
	v_mov_b32_e32 v73, v133
	v_mov_b32_e32 v114, v133
	v_mov_b32_e32 v115, v133
	v_mov_b32_e32 v116, v133
	v_mov_b32_e32 v117, v133
	v_mov_b32_e32 v118, v133
	v_mov_b32_e32 v119, v133
	v_mov_b32_e32 v120, v133
	v_mov_b32_e32 v121, v133
	v_mov_b32_e32 v90, v133
	v_mov_b32_e32 v91, v133
	v_mov_b32_e32 v92, v133
	v_mov_b32_e32 v93, v133
	v_mov_b32_e32 v94, v133
	v_mov_b32_e32 v95, v133
	v_mov_b32_e32 v96, v133
	v_mov_b32_e32 v97, v133
	v_mov_b32_e32 v98, v133
	v_mov_b32_e32 v99, v133
	v_mov_b32_e32 v100, v133
	v_mov_b32_e32 v101, v133
	v_mov_b32_e32 v102, v133
	v_mov_b32_e32 v103, v133
	v_mov_b32_e32 v104, v133
	v_mov_b32_e32 v105, v133
	v_mov_b32_e32 v106, v133
	v_mov_b32_e32 v107, v133
	v_mov_b32_e32 v108, v133
	v_mov_b32_e32 v109, v133
	v_mov_b32_e32 v110, v133
	v_mov_b32_e32 v111, v133
	v_mov_b32_e32 v112, v133
	v_mov_b32_e32 v113, v133
	v_mov_b32_e32 v126, v133
	v_mov_b32_e32 v127, v133
	v_mov_b32_e32 v128, v133
	v_mov_b32_e32 v129, v133
	v_mov_b32_e32 v122, v133
	v_mov_b32_e32 v123, v133
	v_mov_b32_e32 v124, v133
	v_mov_b32_e32 v125, v133
	s_barrier
	s_branch .LBB0_720

; #define PG8_LAS __attribute__((address_space(3)))
; #define PG8_BAR __builtin_amdgcn_s_barrier()
; template <class Epi, class Sched, bool ALIGN_EPI = false, bool SP2 = false, bool PAIR_ACC = false>
; __device__ __forceinline__ void gemm_phase(PG8_LAS unsigned char* lds, const Gemm g, const Sched& S, const Epi& E) {
;     ...
;         PG8_STAGE(PG8_SB(0, 0), cB, voffB); PG8_STAGE(PG8_SB(0, 1), cB + hstep, voffB); PG8_STAGE(PG8_SA(0, 0), cA, voffA); PG8_STAGE(PG8_SA(0, 1), cA + hstep, voffA);
;         if (wr == 1) PG8_BAR;
;         PG8_WAIT_V(2); PG8_BAR;
;         PG8_STAGE(PG8_SB(1, 0), cB + kstep, voffB); PG8_STAGE(PG8_SA(1, 0), cA + kstep, voffA); PG8_STAGE(PG8_SB(1, 1), cB + hstep + kstep, voffB);
;         PG8_WAIT_V(6); PG8_BAR;
;     __device__ __forceinline__ void operator()(const f32x4 (&acc)[2][2][4][2], const Unit& u, int wr, int wc, int fr, int fq) const {
;         const int cl = wc * 32 + 8 * fq, f0 = u.pn * 128 + cl;
;         PG8_LAS float* X = (PG8_LAS float*)xch;
;         f32x4 k0[2], k1[2], k2[2], kb[2];
; #pragma unroll
;         for (int n = 0; n < 2; ++n) { k0[n] = *(const f32x4*)(cw + f0 + 4 * n); k1[n] = *(const f32x4*)(cw + 2816 + f0 + 4 * n); k2[n] = *(const f32x4*)(cw + 2 * 2816 + f0 + 4 * n); kb[n] = *(const f32x4*)(cb + f0 + 4 * n); }
;         if (fr >= 14) {
; #pragma unroll
;             for (int ai = 0; ai < 2; ++ai) { PG8_LAS float* p = X + ((ai * 2 + wr) * 2 + (fr - 14)) * 128 + cl; *(PG8_LAS f32x4*)p = acc[ai][0][3][0]; *(PG8_LAS f32x4*)(p + 4) = acc[ai][0][3][1]; }
;             if (wr == 1) { float* t = TAILA + ((size_t)u.pm * 2 + (fr - 14)) * 2816 + f0; *(f32x4*)t = acc[1][0][3][0]; *(f32x4*)(t + 4) = acc[1][0][3][1]; }
;         }
;         if (wr == 0 && fr < 2) { const size_t o = ((size_t)u.pm * 2 + fr) * 2816 + f0;
;             *(f32x4*)(RAWA + o) = acc[0][0][0][0]; *(f32x4*)(RAWA + o + 4) = acc[0][0][0][1]; *(f32x4*)(RAWU + o) = acc[0][1][0][0]; *(f32x4*)(RAWU + o + 4) = acc[0][1][0][1]; }
;         asm volatile("s_waitcnt lgkmcnt(0)" ::: "memory"); __builtin_amdgcn_s_barrier(); asm volatile("" ::: "memory");
;         const int row0 = u.pm * BM + wr * 64 + fr;
; #pragma unroll
;         for (int ai = 0; ai < 2; ++ai) {
;             f32x4 P[2] = {{0.f, 0.f, 0.f, 0.f}, {0.f, 0.f, 0.f, 0.f}};
;             if (!(ai == 0 && wr == 0) && fr >= 14) { const int pai = (wr == 1) ? ai : ai - 1, pwr = (wr == 1) ? 0 : 1;
.LBB0_828:
	s_add_u32 s18, s6, 0x6b00000
	s_addc_u32 s19, s7, 0
	s_add_u32 s20, s6, 0x200000
	s_addc_u32 s21, s7, 0
	s_add_u32 s28, s6, 0x380000
	s_addc_u32 s29, s7, 0
	s_add_u32 s30, s6, 0x500000
	s_addc_u32 s31, s7, 0
	s_lshl_b32 s6, s41, 5
	s_mov_b64 s[48:49], 0x80
	s_and_b32 s41, s6, 0x60
	s_add_i32 m0, s36, 0x18000
	v_lshl_add_u64 v[8:9], v[8:9], 0, s[48:49]
	s_lshl_b32 s47, s40, 13
	s_lshl_b32 s50, s41, 7
	global_load_lds_dwordx4 v[8:9], off
	v_lshl_add_u64 v[6:7], v[6:7], 0, s[48:49]
	s_add_i32 m0, s36, 0x1a000
	s_add_i32 s45, s36, 0x8000
	s_add_i32 s46, s36, 0xa000
	global_load_lds_dwordx4 v[6:7], off
	v_lshl_add_u64 v[2:3], v[2:3], 0, s[48:49]
	s_mov_b32 m0, s45
	s_add_u32 s6, s38, 0x40080
	global_load_lds_dwordx4 v[2:3], off
	v_lshl_add_u64 v[2:3], v[4:5], 0, s[48:49]
	s_mov_b32 m0, s46
	s_addc_u32 s7, s39, 0
	global_load_lds_dwordx4 v[2:3], off
	s_add_i32 m0, s36, 0x1c000
	v_lshl_add_u64 v[2:3], s[6:7], 0, v[178:179]
	global_load_lds_dwordx4 v[2:3], off
	v_lshl_add_u64 v[2:3], s[6:7], 0, v[174:175]
	s_add_i32 m0, s36, 0x1e000
	v_and_b32_e32 v182, 15, v13
	global_load_lds_dwordx4 v[2:3], off
	s_waitcnt vmcnt(8)
	s_barrier
	v_lshrrev_b32_e32 v2, 1, v13
	v_and_b32_e32 v2, 24, v2
	v_lshlrev_b32_e32 v3, 1, v2
	v_lshlrev_b32_e32 v4, 2, v13
	v_lshl_or_b32 v3, v182, 6, v3
	v_and_b32_e32 v4, 32, v4
	s_cmpk_lt_u32 s9, 0x100
	v_bitop3_b32 v183, v3, s50, v4 bitop3:0xde
	s_cselect_b64 s[50:51], -1, 0
	v_cmp_gt_u32_e32 vcc, 2, v182
	s_sext_i32_i16 s71, s8
	s_lshl_b32 s8, s40, 10
	s_and_b64 s[52:53], s[50:51], vcc
	s_cmpk_gt_u32 s9, 0xff
	v_or_b32_e32 v196, s41, v2
	v_cmp_lt_u32_e64 s[6:7], 13, v182
	v_lshl_add_u32 v2, v182, 9, s8
	s_cselect_b64 s[8:9], -1, 0
	s_and_b64 s[54:55], s[6:7], s[8:9]
	s_cmp_lg_u32 s40, 1
	s_cselect_b64 s[8:9], -1, 0
	v_bitop3_b32 v5, v3, s47, v4 bitop3:0xde
	v_cndmask_b32_e64 v3, 0, -1, s[8:9]
	s_and_b64 s[8:9], s[8:9], exec
	s_cselect_b32 s8, 2, 0
	v_lshlrev_b32_e32 v8, 14, v15
	v_add_u32_e32 v4, s8, v182
	s_cselect_b32 s8, 0, 0x800
	s_ashr_i32 s47, s3, 31
	v_and_b32_e32 v8, 0xffff8000, v8
	s_waitcnt lgkmcnt(0)
	s_add_u32 s56, s12, 0x2c00
	v_lshl_add_u32 v8, v14, 11, v8
	v_and_b32_e32 v9, 1, v15
	s_addc_u32 s57, s13, 0
	v_lshl_or_b32 v8, v9, 6, v8
	s_add_u32 s58, s12, 0x5800
	v_lshl_add_u32 v186, v16, 1, v8
	v_lshlrev_b32_e32 v8, 14, v10
	v_mov_b32_e32 v6, 0xffffe400
	s_addc_u32 s59, s13, 0
	s_add_i32 s9, 0, 0x20000
	v_and_b32_e32 v8, 0xffff8000, v8
	s_waitcnt vmcnt(6)
	v_lshl_add_u32 v4, v4, 9, v6
	v_lshl_add_u32 v6, v196, 2, s9
	v_lshl_add_u32 v8, v11, 11, v8
	v_and_b32_e32 v9, 1, v10
	v_add_u32_e32 v2, 0xffffe400, v2
	v_lshl_add_u32 v3, v3, 11, v6
	v_add_u32_e32 v7, s8, v6
	v_lshl_or_b32 v8, v9, 6, v8
	s_add_i32 s61, 0, 0x10000
	s_add_i32 s74, 0, 0x14000
	v_lshl_or_b32 v173, s40, 6, v182
	v_add_u32_e32 v184, -14, v182
	v_mov_b32_e32 v185, v179
	v_mov_b32_e32 v187, v179
	v_lshl_add_u32 v188, v12, 1, v8
	v_mov_b32_e32 v189, v179
	v_mov_b64_e32 v[190:191], 0x580
	v_mov_b64_e32 v[192:193], 0x57f
	v_add_u32_e32 v197, s61, v183
	v_add_u32_e32 v198, s74, v183
	v_add_u32_e32 v199, 0, v5
	v_add_u32_e32 v206, v6, v2
	s_movk_i32 s75, 0x2c00
	v_add_u32_e32 v207, v3, v4
	s_mov_b32 s60, 0xbfb8aa3b
	s_movk_i32 s76, 0x1600
	v_add_u32_e32 v208, v7, v4
	v_mov_b32_e32 v209, 0xb00
	s_barrier
	s_branch .LBB0_831

; #define PG8_STAGE(bufoff, gbase, voff) do { _Pragma("unroll") for (int _i = 0; _i < 2; ++_i) \
;         __builtin_amdgcn_global_load_lds((const unsigned*)((const char*)(gbase) + (voff)[_i]), (PG8_LAS unsigned*)(lds + (bufoff) + ldsw + _i * 8192), 16, 0, 0); } while (0)
; #define PG8_WAIT_V(n) asm volatile("s_waitcnt vmcnt(" #n ")" ::: "memory")
; #define PG8_BAR __builtin_amdgcn_s_barrier()
; template <class Epi, class Sched, bool ALIGN_EPI = false, bool SP2 = false, bool PAIR_ACC = false>
; __device__ __forceinline__ void gemm_phase(PG8_LAS unsigned char* lds, const Gemm g, const Sched& S, const Epi& E) {
;     ...
;     f32x4 acc[2][2][4][2];
; #pragma unroll
;     for (int a = 0; a < 2; ++a)
; #pragma unroll
;         for (int b = 0; b < 2; ++b)
; #pragma unroll
;             for (int m = 0; m < 4; ++m)
; #pragma unroll
;                 for (int n = 0; n < 2; ++n) acc[a][b][m][n] = (f32x4){0.f, 0.f, 0.f, 0.f};
;     ...
;         PG8_STAGE(PG8_SB(0, 0), cB, voffB); PG8_STAGE(PG8_SB(0, 1), cB + hstep, voffB); PG8_STAGE(PG8_SA(0, 0), cA, voffA); PG8_STAGE(PG8_SA(0, 1), cA + hstep, voffA);
;         if (wr == 1) PG8_BAR;
;         PG8_WAIT_V(2); PG8_BAR;
;         PG8_STAGE(PG8_SB(1, 0), cB + kstep, voffB); PG8_STAGE(PG8_SA(1, 0), cA + kstep, voffA); PG8_STAGE(PG8_SB(1, 1), cB + hstep + kstep, voffB);
;         PG8_WAIT_V(6); PG8_BAR;
.LBB0_923:
	v_and_b32_e32 v167, 15, v168
	s_waitcnt vmcnt(0)
	v_and_b32_e32 v18, 48, v168
	v_lshlrev_b32_e32 v19, 2, v168
	s_mov_b64 s[30:31], 0x80
	s_sext_i32_i8 s18, s7
	s_and_b32 s25, s19, 3
	s_lshl_b32 s7, s24, 13
	v_lshl_or_b32 v18, v167, 6, v18
	v_and_b32_e32 v19, 32, v19
	s_add_i32 m0, s37, 0x18000
	v_lshl_add_u64 v[8:9], v[8:9], 0, s[30:31]
	s_lshl_b32 s23, s24, 6
	v_bitop3_b32 v20, v18, s7, v19 bitop3:0xde
	s_lshl_b32 s7, s25, 12
	global_load_lds_dwordx4 v[8:9], off
	v_lshl_add_u64 v[6:7], v[6:7], 0, s[30:31]
	s_add_i32 m0, s37, 0x1a000
	s_add_i32 s44, s37, 0x8000
	s_add_i32 s45, s37, 0xa000
	global_load_lds_dwordx4 v[6:7], off
	v_lshl_add_u64 v[4:5], v[4:5], 0, s[30:31]
	s_mov_b32 m0, s44
	s_add_u32 s10, s50, 0xb0080
	global_load_lds_dwordx4 v[4:5], off
	v_lshl_add_u64 v[2:3], v[2:3], 0, s[30:31]
	s_mov_b32 m0, s45
	s_addc_u32 s11, s51, 0
	global_load_lds_dwordx4 v[2:3], off
	s_add_i32 m0, s37, 0x1c000
	v_lshl_add_u64 v[2:3], s[10:11], 0, v[132:133]
	global_load_lds_dwordx4 v[2:3], off
	v_lshl_add_u64 v[2:3], s[10:11], 0, v[136:137]
	s_add_i32 m0, s37, 0x1e000
	v_bitop3_b32 v150, v18, s7, v19 bitop3:0xde
	global_load_lds_dwordx4 v[2:3], off
	s_waitcnt vmcnt(8)
	s_barrier
	v_lshrrev_b32_e32 v3, 1, v10
	v_mul_lo_u32 v2, v12, s6
	s_mov_b32 s7, 0xb000
	v_mad_u64_u32 v[2:3], s[10:11], v3, s7, v[2:3]
	v_or_b32_e32 v2, v2, v11
	s_mov_b64 s[8:9], 0xb0080
	v_add_lshl_u32 v2, v2, v13, 1
	v_mov_b32_e32 v3, v133
	v_lshl_add_u64 v[138:139], v[2:3], 0, s[8:9]
	v_lshrrev_b32_e32 v3, 1, v14
	v_mul_lo_u32 v2, v15, s6
	v_mad_u64_u32 v[2:3], s[6:7], v3, s7, v[2:3]
	s_waitcnt vmcnt(6)
	v_or_b32_e32 v2, v2, v16
	v_add_lshl_u32 v2, v2, v17, 1
	v_mov_b32_e32 v3, v133
	v_or_b32_e32 v166, s23, v167
	v_lshl_add_u64 v[140:141], v[2:3], 0, s[8:9]
	v_mov_b64_e32 v[142:143], 0x100
	v_mov_b64_e32 v[144:145], 0xff
	s_add_i32 s46, 0, 0x10000
	s_add_i32 s47, 0, 0x14000
	v_add_u32_e32 v151, 0, v20
	v_mov_b32_e32 v2, v133
	v_mov_b32_e32 v4, v133
	v_mov_b32_e32 v5, v133
	v_mov_b32_e32 v6, v133
	v_mov_b32_e32 v7, v133
	v_mov_b32_e32 v8, v133
	v_mov_b32_e32 v9, v133
	v_mov_b32_e32 v18, v133
	v_mov_b32_e32 v19, v133
	v_mov_b32_e32 v20, v133
	v_mov_b32_e32 v21, v133
	v_mov_b32_e32 v22, v133
	v_mov_b32_e32 v23, v133
	v_mov_b32_e32 v24, v133
	v_mov_b32_e32 v25, v133
	v_mov_b32_e32 v34, v133
	v_mov_b32_e32 v35, v133
	v_mov_b32_e32 v36, v133
	v_mov_b32_e32 v37, v133
	v_mov_b32_e32 v38, v133
	v_mov_b32_e32 v39, v133
	v_mov_b32_e32 v40, v133
	v_mov_b32_e32 v41, v133
	v_mov_b32_e32 v106, v133
	v_mov_b32_e32 v107, v133
	v_mov_b32_e32 v108, v133
	v_mov_b32_e32 v109, v133
	v_mov_b32_e32 v118, v133
	v_mov_b32_e32 v119, v133
	v_mov_b32_e32 v120, v133
	v_mov_b32_e32 v121, v133
	v_mov_b32_e32 v10, v133
	v_mov_b32_e32 v11, v133
	v_mov_b32_e32 v12, v133
	v_mov_b32_e32 v13, v133
	v_mov_b32_e32 v14, v133
	v_mov_b32_e32 v15, v133
	v_mov_b32_e32 v16, v133
	v_mov_b32_e32 v17, v133
	v_mov_b32_e32 v26, v133
	v_mov_b32_e32 v27, v133
	v_mov_b32_e32 v28, v133
	v_mov_b32_e32 v29, v133
	v_mov_b32_e32 v30, v133
	v_mov_b32_e32 v31, v133
	v_mov_b32_e32 v32, v133
	v_mov_b32_e32 v33, v133
	v_mov_b32_e32 v66, v133
	v_mov_b32_e32 v67, v133
	v_mov_b32_e32 v68, v133
	v_mov_b32_e32 v69, v133
	v_mov_b32_e32 v86, v133
	v_mov_b32_e32 v87, v133
	v_mov_b32_e32 v88, v133
	v_mov_b32_e32 v89, v133
	v_mov_b32_e32 v122, v133
	v_mov_b32_e32 v123, v133
	v_mov_b32_e32 v124, v133
	v_mov_b32_e32 v125, v133
	v_mov_b32_e32 v126, v133
	v_mov_b32_e32 v127, v133
	v_mov_b32_e32 v128, v133
	v_mov_b32_e32 v129, v133
	v_mov_b32_e32 v94, v133
	v_mov_b32_e32 v95, v133
	v_mov_b32_e32 v96, v133
	v_mov_b32_e32 v97, v133
	v_mov_b32_e32 v102, v133
	v_mov_b32_e32 v103, v133
	v_mov_b32_e32 v104, v133
	v_mov_b32_e32 v105, v133
	v_mov_b32_e32 v70, v133
	v_mov_b32_e32 v71, v133
	v_mov_b32_e32 v72, v133
	v_mov_b32_e32 v73, v133
	v_mov_b32_e32 v78, v133
	v_mov_b32_e32 v79, v133
	v_mov_b32_e32 v80, v133
	v_mov_b32_e32 v81, v133
	v_mov_b32_e32 v42, v133
	v_mov_b32_e32 v43, v133
	v_mov_b32_e32 v44, v133
	v_mov_b32_e32 v45, v133
	v_mov_b32_e32 v50, v133
	v_mov_b32_e32 v51, v133
	v_mov_b32_e32 v52, v133
	v_mov_b32_e32 v53, v133
	v_mov_b32_e32 v46, v133
	v_mov_b32_e32 v47, v133
	v_mov_b32_e32 v48, v133
	v_mov_b32_e32 v49, v133
	v_mov_b32_e32 v54, v133
	v_mov_b32_e32 v55, v133
	v_mov_b32_e32 v56, v133
	v_mov_b32_e32 v57, v133
	v_mov_b32_e32 v110, v133
	v_mov_b32_e32 v111, v133
	v_mov_b32_e32 v112, v133
	v_mov_b32_e32 v113, v133
	v_mov_b32_e32 v114, v133
	v_mov_b32_e32 v115, v133
	v_mov_b32_e32 v116, v133
	v_mov_b32_e32 v117, v133
	v_mov_b32_e32 v90, v133
	v_mov_b32_e32 v91, v133
	v_mov_b32_e32 v92, v133
	v_mov_b32_e32 v93, v133
	v_mov_b32_e32 v98, v133
	v_mov_b32_e32 v99, v133
	v_mov_b32_e32 v100, v133
	v_mov_b32_e32 v101, v133
	v_mov_b32_e32 v74, v133
	v_mov_b32_e32 v75, v133
	v_mov_b32_e32 v76, v133
	v_mov_b32_e32 v77, v133
	v_mov_b32_e32 v82, v133
	v_mov_b32_e32 v83, v133
	v_mov_b32_e32 v84, v133
	v_mov_b32_e32 v85, v133
	v_mov_b32_e32 v62, v133
	v_mov_b32_e32 v63, v133
	v_mov_b32_e32 v64, v133
	v_mov_b32_e32 v65, v133
	v_mov_b32_e32 v58, v133
	v_mov_b32_e32 v59, v133
	v_mov_b32_e32 v60, v133
	v_mov_b32_e32 v61, v133
	s_barrier
	s_branch .LBB0_926

; #define PG8_STAGE(bufoff, gbase, voff) do { _Pragma("unroll") for (int _i = 0; _i < 2; ++_i) \
;         __builtin_amdgcn_global_load_lds((const unsigned*)((const char*)(gbase) + (voff)[_i]), (PG8_LAS unsigned*)(lds + (bufoff) + ldsw + _i * 8192), 16, 0, 0); } while (0)
; #define PG8_WAIT_V(n) asm volatile("s_waitcnt vmcnt(" #n ")" ::: "memory")
; #define PG8_BAR __builtin_amdgcn_s_barrier()
; template <class Epi, class Sched, bool ALIGN_EPI = false, bool SP2 = false, bool PAIR_ACC = false>
; __device__ __forceinline__ void gemm_phase(PG8_LAS unsigned char* lds, const Gemm g, const Sched& S, const Epi& E) {
;     ...
;         PG8_STAGE(PG8_SB(0, 0), cB, voffB); PG8_STAGE(PG8_SB(0, 1), cB + hstep, voffB); PG8_STAGE(PG8_SA(0, 0), cA, voffA); PG8_STAGE(PG8_SA(0, 1), cA + hstep, voffA);
;         if (wr == 1) PG8_BAR;
;         PG8_WAIT_V(2); PG8_BAR;
;         PG8_STAGE(PG8_SB(1, 0), cB + kstep, voffB); PG8_STAGE(PG8_SA(1, 0), cA + kstep, voffA); PG8_STAGE(PG8_SB(1, 1), cB + hstep + kstep, voffB);
;         PG8_WAIT_V(6); PG8_BAR;
;     __device__ __forceinline__ void operator()(const f32x4 (&acc)[2][2][4][2], const Unit& u, int wr, int wc, int fr, int fq) const {
;     ...
;         const bool ropelane = ((wc & 1) == 0) && (fq < 2);
;         const float sgn = (fq == 0) ? -1.f : 1.f;
.LBB0_1078:
	s_add_u32 s40, s28, 0x100000
	s_addc_u32 s41, s29, 0
	s_add_u32 s46, s28, 0xf400000
	s_mov_b64 s[48:49], 0x80
	s_addc_u32 s47, s29, 0
	s_and_b32 s5, s5, 3
	s_add_i32 m0, s73, 0x18000
	v_lshl_add_u64 v[8:9], v[8:9], 0, s[48:49]
	s_lshl_b32 s9, s8, 13
	s_lshl_b32 s15, s5, 12
	global_load_lds_dwordx4 v[8:9], off
	v_lshl_add_u64 v[6:7], v[6:7], 0, s[48:49]
	s_add_i32 m0, s73, 0x1a000
	s_add_i32 s36, s73, 0x8000
	s_add_i32 s37, s73, 0xa000
	global_load_lds_dwordx4 v[6:7], off
	v_lshl_add_u64 v[2:3], v[2:3], 0, s[48:49]
	s_mov_b32 m0, s36
	s_add_u32 s10, s16, 0x40080
	global_load_lds_dwordx4 v[2:3], off
	v_lshl_add_u64 v[2:3], v[4:5], 0, s[48:49]
	s_mov_b32 m0, s37
	s_addc_u32 s11, s17, 0
	global_load_lds_dwordx4 v[2:3], off
	s_add_i32 m0, s73, 0x1c000
	v_lshl_add_u64 v[2:3], s[10:11], 0, v[148:149]
	global_load_lds_dwordx4 v[2:3], off
	v_lshl_add_u64 v[2:3], s[10:11], 0, v[152:153]
	s_add_i32 m0, s73, 0x1e000
	v_and_b32_e32 v17, 15, v10
	global_load_lds_dwordx4 v[2:3], off
	s_waitcnt vmcnt(8)
	s_barrier
	v_bfe_u32 v2, v10, 4, 2
	v_lshlrev_b32_e32 v3, 3, v2
	v_lshlrev_b32_e32 v4, 4, v2
	v_lshlrev_b32_e32 v5, 2, v10
	v_lshl_or_b32 v156, s5, 5, v3
	v_lshl_or_b32 v4, v17, 6, v4
	v_and_b32_e32 v5, 32, v5
	v_lshlrev_b32_e32 v154, 1, v156
	v_lshl_or_b32 v157, s8, 6, v17
	v_bitop3_b32 v6, v4, s9, v5 bitop3:0xde
	v_cmp_gt_u32_e64 s[8:9], 2, v2
	v_cmp_eq_u32_e64 s[10:11], 0, v2
	v_lshl_add_u64 v[2:3], s[28:29], 0, v[154:155]
	s_mov_b64 s[20:21], 0xd300000
	v_lshl_add_u64 v[162:163], v[2:3], 0, s[20:21]
	s_mov_b64 s[20:21], 0x6b00000
	v_lshl_add_u64 v[164:165], v[2:3], 0, s[20:21]
	s_mov_b64 s[20:21], 0x8b00000
	s_cmpk_lt_u32 s4, 0x100
	v_lshl_add_u64 v[166:167], v[2:3], 0, s[20:21]
	s_mov_b64 s[20:21], 0x8f00000
	s_cselect_b64 s[50:51], -1, 0
	s_bitcmp0_b32 s4, 6
	v_lshl_add_u64 v[168:169], v[2:3], 0, s[20:21]
	v_lshlrev_b32_e32 v2, 14, v11
	s_cselect_b64 s[52:53], -1, 0
	s_lshl_b32 s4, s5, 1
	v_and_b32_e32 v2, 0xffff8000, v2
	s_or_b32 s4, s4, 0xffffffb8
	s_ashr_i32 s5, s2, 3
	v_lshl_add_u32 v2, v12, 11, v2
	v_and_b32_e32 v3, 1, v11
	s_cmp_gt_i32 s5, 7
	v_lshl_or_b32 v2, v3, 6, v2
	v_bitop3_b32 v194, v4, s15, v5 bitop3:0xde
	s_cselect_b64 s[54:55], -1, 0
	s_add_i32 s15, s5, -8
	v_lshl_add_u32 v170, v13, 1, v2
	v_lshlrev_b32_e32 v2, 14, v14
	v_writelane_b32 v246, s15, 8
	v_and_b32_e32 v2, 0xffff8000, v2
	s_waitcnt vmcnt(6)
	v_readlane_b32 s15, v246, 2
	v_lshl_add_u32 v2, v15, 11, v2
	v_and_b32_e32 v3, 1, v14
	v_cndmask_b32_e64 v158, 1.0, -1.0, s[10:11]
	s_and_b32 s25, s15, 56
	s_and_b32 s15, s5, 7
	v_lshl_or_b32 v2, v3, 6, v2
	s_add_i32 s34, 0, 0x10000
	s_add_i32 s35, 0, 0x14000
	v_mov_b32_e32 v159, v158
	v_mov_b32_e32 v160, v158
	v_mov_b32_e32 v161, v158
	s_or_b32 s24, s25, s15
	s_add_i32 s25, s25, s5
	v_mov_b32_e32 v171, v155
	v_lshl_add_u32 v172, v16, 1, v2
	v_mov_b32_e32 v173, v155
	s_mov_b64 s[56:57], 0x100
	v_add_u32_e32 v195, s34, v194
	v_add_u32_e32 v196, s35, v194
	v_add_u32_e32 v197, 0, v6
	s_mov_b32 s58, 0xbfb8aa3b
	s_mov_b32 s60, 0x3e6d3388
	s_mov_b32 s62, 0x3f07dc22
	s_mov_b32 s64, 0xbf3a00e3
	s_mov_b32 s66, 0x3f35f0e3
	s_mov_b32 s68, 0xbe11a98e
	s_mov_b32 s70, 0x3e027906
	s_mov_b32 s72, 0xbf38aa3b
	s_mov_b32 s74, 0x3e38aa3b
	v_mov_b64_e32 v[174:175], 0x53f
	v_mbcnt_hi_u32_b32 v198, -1, v1
	s_mov_b32 s15, 0
	s_barrier
	s_branch .LBB0_1081

; #define PG8_STAGE(bufoff, gbase, voff) do { _Pragma("unroll") for (int _i = 0; _i < 2; ++_i) \
;         __builtin_amdgcn_global_load_lds((const unsigned*)((const char*)(gbase) + (voff)[_i]), (PG8_LAS unsigned*)(lds + (bufoff) + ldsw + _i * 8192), 16, 0, 0); } while (0)
; #define PG8_WAIT_V(n) asm volatile("s_waitcnt vmcnt(" #n ")" ::: "memory")
; #define PG8_BAR __builtin_amdgcn_s_barrier()
; template <class Epi, class Sched, bool ALIGN_EPI = false, bool SP2 = false, bool PAIR_ACC = false>
; __device__ __forceinline__ void gemm_phase(PG8_LAS unsigned char* lds, const Gemm g, const Sched& S, const Epi& E) {
;     ...
;     f32x4 acc[2][2][4][2];
; #pragma unroll
;     for (int a = 0; a < 2; ++a)
; #pragma unroll
;         for (int b = 0; b < 2; ++b)
; #pragma unroll
;             for (int m = 0; m < 4; ++m)
; #pragma unroll
;                 for (int n = 0; n < 2; ++n) acc[a][b][m][n] = (f32x4){0.f, 0.f, 0.f, 0.f};
;     ...
;         PG8_STAGE(PG8_SB(0, 0), cB, voffB); PG8_STAGE(PG8_SB(0, 1), cB + hstep, voffB); PG8_STAGE(PG8_SA(0, 0), cA, voffA); PG8_STAGE(PG8_SA(0, 1), cA + hstep, voffA);
;         if (wr == 1) PG8_BAR;
;         PG8_WAIT_V(2); PG8_BAR;
;         PG8_STAGE(PG8_SB(1, 0), cB + kstep, voffB); PG8_STAGE(PG8_SA(1, 0), cA + kstep, voffA); PG8_STAGE(PG8_SB(1, 1), cB + hstep + kstep, voffB);
;         PG8_WAIT_V(6); PG8_BAR;
.LBB0_1476:
	s_add_u32 s12, s6, 0x2b00000
	s_addc_u32 s13, s7, 0
	s_add_u32 s14, s6, 0xb300000
	v_lshrrev_b32_e32 v18, 1, v10
	s_addc_u32 s15, s7, 0
	v_and_b32_e32 v18, 24, v18
	s_add_u32 s16, s6, 0xd300000
	v_and_b32_e32 v17, 15, v10
	v_lshlrev_b32_e32 v19, 1, v18
	v_lshlrev_b32_e32 v10, 2, v10
	s_addc_u32 s17, s7, 0
	v_lshl_or_b32 v198, s8, 6, v17
	v_lshl_or_b32 v17, v17, 6, v19
	s_lshl_b32 s6, s8, 13
	v_and_b32_e32 v10, 32, v10
	v_bitop3_b32 v19, v17, s6, v10 bitop3:0xde
	s_lshl_b32 s6, s9, 5
	s_mov_b64 s[18:19], 0x80
	s_and_b32 s8, s6, 0x60
	s_add_i32 m0, s35, 0x18000
	v_lshl_add_u64 v[8:9], v[8:9], 0, s[18:19]
	s_lshl_b32 s6, s8, 7
	global_load_lds_dwordx4 v[8:9], off
	v_lshl_add_u64 v[6:7], v[6:7], 0, s[18:19]
	s_add_i32 m0, s35, 0x1a000
	s_add_i32 s45, s35, 0x8000
	s_add_i32 s50, s35, 0xa000
	v_bitop3_b32 v199, v17, s6, v10 bitop3:0xde
	global_load_lds_dwordx4 v[6:7], off
	v_lshl_add_u64 v[2:3], v[2:3], 0, s[18:19]
	s_mov_b32 m0, s45
	s_add_u32 s6, s46, 0x40080
	global_load_lds_dwordx4 v[2:3], off
	v_lshl_add_u64 v[2:3], v[4:5], 0, s[18:19]
	s_mov_b32 m0, s50
	s_addc_u32 s7, s47, 0
	global_load_lds_dwordx4 v[2:3], off
	s_add_i32 m0, s35, 0x1c000
	v_lshl_add_u64 v[2:3], s[6:7], 0, v[160:161]
	global_load_lds_dwordx4 v[2:3], off
	v_lshl_add_u64 v[2:3], s[6:7], 0, v[164:165]
	s_add_i32 m0, s35, 0x1e000
	s_cmpk_lt_u32 s20, 0x100
	global_load_lds_dwordx4 v[2:3], off
	s_waitcnt vmcnt(8)
	s_barrier
	v_lshlrev_b32_e32 v2, 14, v11
	v_and_b32_e32 v2, 0xffff8000, v2
	v_lshl_add_u32 v2, v12, 11, v2
	v_and_b32_e32 v3, 1, v11
	v_lshl_or_b32 v2, v3, 6, v2
	v_lshl_add_u32 v168, v13, 1, v2
	v_lshlrev_b32_e32 v2, 14, v14
	v_and_b32_e32 v2, 0xffff8000, v2
	s_waitcnt vmcnt(6)
	v_lshl_add_u32 v2, v15, 11, v2
	v_and_b32_e32 v3, 1, v14
	v_lshl_or_b32 v2, v3, 6, v2
	s_cselect_b64 s[20:21], -1, 0
	v_or_b32_e32 v200, s8, v18
	v_mov_b32_e32 v169, v167
	v_lshl_add_u32 v170, v16, 1, v2
	v_mov_b32_e32 v171, v167
	v_mov_b64_e32 v[172:173], 0x100
	v_mov_b64_e32 v[174:175], 0xff
	s_add_i32 s51, 0, 0x10000
	s_add_i32 s52, 0, 0x14000
	v_add_u32_e32 v201, 0, v19
	v_mov_b32_e32 v2, v167
	v_mov_b32_e32 v3, v167
	v_mov_b32_e32 v4, v167
	v_mov_b32_e32 v5, v167
	v_mov_b32_e32 v6, v167
	v_mov_b32_e32 v7, v167
	v_mov_b32_e32 v8, v167
	v_mov_b32_e32 v9, v167
	v_mov_b32_e32 v10, v167
	v_mov_b32_e32 v11, v167
	v_mov_b32_e32 v12, v167
	v_mov_b32_e32 v13, v167
	v_mov_b32_e32 v14, v167
	v_mov_b32_e32 v15, v167
	v_mov_b32_e32 v16, v167
	v_mov_b32_e32 v17, v167
	v_mov_b32_e32 v18, v167
	v_mov_b32_e32 v19, v167
	v_mov_b32_e32 v20, v167
	v_mov_b32_e32 v21, v167
	v_mov_b32_e32 v22, v167
	v_mov_b32_e32 v23, v167
	v_mov_b32_e32 v24, v167
	v_mov_b32_e32 v25, v167
	v_mov_b32_e32 v26, v167
	v_mov_b32_e32 v27, v167
	v_mov_b32_e32 v28, v167
	v_mov_b32_e32 v29, v167
	v_mov_b32_e32 v30, v167
	v_mov_b32_e32 v31, v167
	v_mov_b32_e32 v32, v167
	v_mov_b32_e32 v33, v167
	v_mov_b32_e32 v34, v167
	v_mov_b32_e32 v35, v167
	v_mov_b32_e32 v36, v167
	v_mov_b32_e32 v37, v167
	v_mov_b32_e32 v38, v167
	v_mov_b32_e32 v39, v167
	v_mov_b32_e32 v40, v167
	v_mov_b32_e32 v41, v167
	v_mov_b32_e32 v42, v167
	v_mov_b32_e32 v43, v167
	v_mov_b32_e32 v44, v167
	v_mov_b32_e32 v45, v167
	v_mov_b32_e32 v46, v167
	v_mov_b32_e32 v47, v167
	v_mov_b32_e32 v48, v167
	v_mov_b32_e32 v49, v167
	v_mov_b32_e32 v50, v167
	v_mov_b32_e32 v51, v167
	v_mov_b32_e32 v52, v167
	v_mov_b32_e32 v53, v167
	v_mov_b32_e32 v54, v167
	v_mov_b32_e32 v55, v167
	v_mov_b32_e32 v56, v167
	v_mov_b32_e32 v57, v167
	v_mov_b32_e32 v58, v167
	v_mov_b32_e32 v59, v167
	v_mov_b32_e32 v60, v167
	v_mov_b32_e32 v61, v167
	v_mov_b32_e32 v62, v167
	v_mov_b32_e32 v63, v167
	v_mov_b32_e32 v64, v167
	v_mov_b32_e32 v65, v167
	v_mov_b32_e32 v66, v167
	v_mov_b32_e32 v67, v167
	v_mov_b32_e32 v68, v167
	v_mov_b32_e32 v69, v167
	v_mov_b32_e32 v70, v167
	v_mov_b32_e32 v71, v167
	v_mov_b32_e32 v72, v167
	v_mov_b32_e32 v73, v167
	v_mov_b32_e32 v74, v167
	v_mov_b32_e32 v75, v167
	v_mov_b32_e32 v76, v167
	v_mov_b32_e32 v77, v167
	v_mov_b32_e32 v78, v167
	v_mov_b32_e32 v79, v167
	v_mov_b32_e32 v80, v167
	v_mov_b32_e32 v81, v167
	v_mov_b32_e32 v82, v167
	v_mov_b32_e32 v83, v167
	v_mov_b32_e32 v84, v167
	v_mov_b32_e32 v85, v167
	v_mov_b32_e32 v86, v167
	v_mov_b32_e32 v87, v167
	v_mov_b32_e32 v88, v167
	v_mov_b32_e32 v89, v167
	v_mov_b32_e32 v90, v167
	v_mov_b32_e32 v91, v167
	v_mov_b32_e32 v92, v167
	v_mov_b32_e32 v93, v167
	v_mov_b32_e32 v94, v167
	v_mov_b32_e32 v95, v167
	v_mov_b32_e32 v96, v167
	v_mov_b32_e32 v97, v167
	v_mov_b32_e32 v98, v167
	v_mov_b32_e32 v99, v167
	v_mov_b32_e32 v100, v167
	v_mov_b32_e32 v101, v167
	v_mov_b32_e32 v102, v167
	v_mov_b32_e32 v103, v167
	v_mov_b32_e32 v104, v167
	v_mov_b32_e32 v105, v167
	v_mov_b32_e32 v106, v167
	v_mov_b32_e32 v107, v167
	v_mov_b32_e32 v108, v167
	v_mov_b32_e32 v109, v167
	v_mov_b32_e32 v110, v167
	v_mov_b32_e32 v111, v167
	v_mov_b32_e32 v112, v167
	v_mov_b32_e32 v113, v167
	v_mov_b32_e32 v114, v167
	v_mov_b32_e32 v115, v167
	v_mov_b32_e32 v116, v167
	v_mov_b32_e32 v117, v167
	v_mov_b32_e32 v118, v167
	v_mov_b32_e32 v119, v167
	v_mov_b32_e32 v120, v167
	v_mov_b32_e32 v121, v167
	v_mov_b32_e32 v122, v167
	v_mov_b32_e32 v123, v167
	v_mov_b32_e32 v124, v167
	v_mov_b32_e32 v125, v167
	v_mov_b32_e32 v126, v167
	v_mov_b32_e32 v127, v167
	v_mov_b32_e32 v128, v167
	v_mov_b32_e32 v129, v167
	s_barrier
	s_branch .LBB0_1479

; #define PG8_STAGE(bufoff, gbase, voff) do { _Pragma("unroll") for (int _i = 0; _i < 2; ++_i) \
;         __builtin_amdgcn_global_load_lds((const unsigned*)((const char*)(gbase) + (voff)[_i]), (PG8_LAS unsigned*)(lds + (bufoff) + ldsw + _i * 8192), 16, 0, 0); } while (0)
; #define PG8_WAIT_V(n) asm volatile("s_waitcnt vmcnt(" #n ")" ::: "memory")
; #define PG8_BAR __builtin_amdgcn_s_barrier()
; template <class Epi, class Sched, bool ALIGN_EPI = false, bool SP2 = false, bool PAIR_ACC = false>
; __device__ __forceinline__ void gemm_phase(PG8_LAS unsigned char* lds, const Gemm g, const Sched& S, const Epi& E) {
;     ...
;     f32x4 acc[2][2][4][2];
; #pragma unroll
;     for (int a = 0; a < 2; ++a)
; #pragma unroll
;         for (int b = 0; b < 2; ++b)
; #pragma unroll
;             for (int m = 0; m < 4; ++m)
; #pragma unroll
;                 for (int n = 0; n < 2; ++n) acc[a][b][m][n] = (f32x4){0.f, 0.f, 0.f, 0.f};
;     ...
;         PG8_STAGE(PG8_SB(0, 0), cB, voffB); PG8_STAGE(PG8_SB(0, 1), cB + hstep, voffB); PG8_STAGE(PG8_SA(0, 0), cA, voffA); PG8_STAGE(PG8_SA(0, 1), cA + hstep, voffA);
;         if (wr == 1) PG8_BAR;
;         PG8_WAIT_V(2); PG8_BAR;
;         PG8_STAGE(PG8_SB(1, 0), cB + kstep, voffB); PG8_STAGE(PG8_SA(1, 0), cA + kstep, voffA); PG8_STAGE(PG8_SB(1, 1), cB + hstep + kstep, voffB);
;         PG8_WAIT_V(6); PG8_BAR;
.LBB0_1620:
	v_and_b32_e32 v167, 15, v168
	v_and_b32_e32 v16, 48, v168
	v_lshlrev_b32_e32 v17, 2, v168
	s_mov_b64 s[22:23], 0x80
	s_sext_i32_i8 s10, s6
	s_and_b32 s19, s11, 3
	s_lshl_b32 s6, s24, 13
	v_lshl_or_b32 v16, v167, 6, v16
	v_and_b32_e32 v17, 32, v17
	s_add_i32 m0, s50, 0x18000
	v_lshl_add_u64 v[8:9], v[8:9], 0, s[22:23]
	s_lshl_b32 s5, s24, 6
	v_bitop3_b32 v18, v16, s6, v17 bitop3:0xde
	s_lshl_b32 s6, s19, 12
	global_load_lds_dwordx4 v[8:9], off
	v_lshl_add_u64 v[6:7], v[6:7], 0, s[22:23]
	s_add_i32 m0, s50, 0x1a000
	s_add_i32 s55, s50, 0x8000
	s_add_i32 s56, s50, 0xa000
	global_load_lds_dwordx4 v[6:7], off
	v_lshl_add_u64 v[4:5], v[4:5], 0, s[22:23]
	s_mov_b32 m0, s55
	s_add_u32 s8, s44, 0x40080
	global_load_lds_dwordx4 v[4:5], off
	v_lshl_add_u64 v[2:3], v[2:3], 0, s[22:23]
	s_mov_b32 m0, s56
	s_addc_u32 s9, s45, 0
	global_load_lds_dwordx4 v[2:3], off
	s_add_i32 m0, s50, 0x1c000
	v_lshl_add_u64 v[2:3], s[8:9], 0, v[132:133]
	global_load_lds_dwordx4 v[2:3], off
	v_lshl_add_u64 v[2:3], s[8:9], 0, v[136:137]
	s_add_i32 m0, s50, 0x1e000
	v_bitop3_b32 v150, v16, s6, v17 bitop3:0xde
	global_load_lds_dwordx4 v[2:3], off
	s_waitcnt vmcnt(8)
	s_barrier
	v_lshlrev_b32_e32 v2, 14, v10
	v_and_b32_e32 v2, 0xffff8000, v2
	v_lshl_add_u32 v2, v11, 11, v2
	v_and_b32_e32 v3, 1, v10
	v_lshl_or_b32 v2, v3, 6, v2
	s_mov_b64 s[6:7], 0x40080
	v_lshl_add_u32 v2, v12, 1, v2
	v_mov_b32_e32 v3, v133
	v_lshl_add_u64 v[138:139], v[2:3], 0, s[6:7]
	v_lshlrev_b32_e32 v2, 14, v13
	v_and_b32_e32 v2, 0xffff8000, v2
	v_lshl_add_u32 v2, v14, 11, v2
	v_and_b32_e32 v3, 1, v13
	s_waitcnt vmcnt(6)
	v_lshl_or_b32 v2, v3, 6, v2
	v_lshl_add_u32 v2, v15, 1, v2
	v_mov_b32_e32 v3, v133
	v_or_b32_e32 v166, s5, v167
	v_lshl_add_u64 v[140:141], v[2:3], 0, s[6:7]
	v_mov_b64_e32 v[142:143], 0x100
	v_mov_b64_e32 v[144:145], 0xff
	s_add_i32 s57, 0, 0x10000
	s_add_i32 s58, 0, 0x14000
	v_add_u32_e32 v151, 0, v18
	v_mov_b32_e32 v2, v133
	v_mov_b32_e32 v4, v133
	v_mov_b32_e32 v5, v133
	v_mov_b32_e32 v6, v133
	v_mov_b32_e32 v7, v133
	v_mov_b32_e32 v8, v133
	v_mov_b32_e32 v9, v133
	v_mov_b32_e32 v18, v133
	v_mov_b32_e32 v19, v133
	v_mov_b32_e32 v20, v133
	v_mov_b32_e32 v21, v133
	v_mov_b32_e32 v22, v133
	v_mov_b32_e32 v23, v133
	v_mov_b32_e32 v24, v133
	v_mov_b32_e32 v25, v133
	v_mov_b32_e32 v34, v133
	v_mov_b32_e32 v35, v133
	v_mov_b32_e32 v36, v133
	v_mov_b32_e32 v37, v133
	v_mov_b32_e32 v38, v133
	v_mov_b32_e32 v39, v133
	v_mov_b32_e32 v40, v133
	v_mov_b32_e32 v41, v133
	v_mov_b32_e32 v110, v133
	v_mov_b32_e32 v111, v133
	v_mov_b32_e32 v112, v133
	v_mov_b32_e32 v113, v133
	v_mov_b32_e32 v118, v133
	v_mov_b32_e32 v119, v133
	v_mov_b32_e32 v120, v133
	v_mov_b32_e32 v121, v133
	v_mov_b32_e32 v10, v133
	v_mov_b32_e32 v11, v133
	v_mov_b32_e32 v12, v133
	v_mov_b32_e32 v13, v133
	v_mov_b32_e32 v14, v133
	v_mov_b32_e32 v15, v133
	v_mov_b32_e32 v16, v133
	v_mov_b32_e32 v17, v133
	v_mov_b32_e32 v26, v133
	v_mov_b32_e32 v27, v133
	v_mov_b32_e32 v28, v133
	v_mov_b32_e32 v29, v133
	v_mov_b32_e32 v30, v133
	v_mov_b32_e32 v31, v133
	v_mov_b32_e32 v32, v133
	v_mov_b32_e32 v33, v133
	v_mov_b32_e32 v82, v133
	v_mov_b32_e32 v83, v133
	v_mov_b32_e32 v84, v133
	v_mov_b32_e32 v85, v133
	v_mov_b32_e32 v86, v133
	v_mov_b32_e32 v87, v133
	v_mov_b32_e32 v88, v133
	v_mov_b32_e32 v89, v133
	v_mov_b32_e32 v122, v133
	v_mov_b32_e32 v123, v133
	v_mov_b32_e32 v124, v133
	v_mov_b32_e32 v125, v133
	v_mov_b32_e32 v126, v133
	v_mov_b32_e32 v127, v133
	v_mov_b32_e32 v128, v133
	v_mov_b32_e32 v129, v133
	v_mov_b32_e32 v94, v133
	v_mov_b32_e32 v95, v133
	v_mov_b32_e32 v96, v133
	v_mov_b32_e32 v97, v133
	v_mov_b32_e32 v102, v133
	v_mov_b32_e32 v103, v133
	v_mov_b32_e32 v104, v133
	v_mov_b32_e32 v105, v133
	v_mov_b32_e32 v66, v133
	v_mov_b32_e32 v67, v133
	v_mov_b32_e32 v68, v133
	v_mov_b32_e32 v69, v133
	v_mov_b32_e32 v74, v133
	v_mov_b32_e32 v75, v133
	v_mov_b32_e32 v76, v133
	v_mov_b32_e32 v77, v133
	v_mov_b32_e32 v42, v133
	v_mov_b32_e32 v43, v133
	v_mov_b32_e32 v44, v133
	v_mov_b32_e32 v45, v133
	v_mov_b32_e32 v50, v133
	v_mov_b32_e32 v51, v133
	v_mov_b32_e32 v52, v133
	v_mov_b32_e32 v53, v133
	v_mov_b32_e32 v46, v133
	v_mov_b32_e32 v47, v133
	v_mov_b32_e32 v48, v133
	v_mov_b32_e32 v49, v133
	v_mov_b32_e32 v54, v133
	v_mov_b32_e32 v55, v133
	v_mov_b32_e32 v56, v133
	v_mov_b32_e32 v57, v133
	v_mov_b32_e32 v106, v133
	v_mov_b32_e32 v107, v133
	v_mov_b32_e32 v108, v133
	v_mov_b32_e32 v109, v133
	v_mov_b32_e32 v114, v133
	v_mov_b32_e32 v115, v133
	v_mov_b32_e32 v116, v133
	v_mov_b32_e32 v117, v133
	v_mov_b32_e32 v90, v133
	v_mov_b32_e32 v91, v133
	v_mov_b32_e32 v92, v133
	v_mov_b32_e32 v93, v133
	v_mov_b32_e32 v98, v133
	v_mov_b32_e32 v99, v133
	v_mov_b32_e32 v100, v133
	v_mov_b32_e32 v101, v133
	v_mov_b32_e32 v70, v133
	v_mov_b32_e32 v71, v133
	v_mov_b32_e32 v72, v133
	v_mov_b32_e32 v73, v133
	v_mov_b32_e32 v78, v133
	v_mov_b32_e32 v79, v133
	v_mov_b32_e32 v80, v133
	v_mov_b32_e32 v81, v133
	v_mov_b32_e32 v62, v133
	v_mov_b32_e32 v63, v133
	v_mov_b32_e32 v64, v133
	v_mov_b32_e32 v65, v133
	v_mov_b32_e32 v58, v133
	v_mov_b32_e32 v59, v133
	v_mov_b32_e32 v60, v133
	v_mov_b32_e32 v61, v133
	s_barrier
	s_branch .LBB0_1623

; #define PG8_LAS __attribute__((address_space(3)))
; #define PG8_BAR __builtin_amdgcn_s_barrier()
; template <class Epi, class Sched, bool ALIGN_EPI = false, bool SP2 = false, bool PAIR_ACC = false>
; __device__ __forceinline__ void gemm_phase(PG8_LAS unsigned char* lds, const Gemm g, const Sched& S, const Epi& E) {
;     ...
;         PG8_STAGE(PG8_SB(0, 0), cB, voffB); PG8_STAGE(PG8_SB(0, 1), cB + hstep, voffB); PG8_STAGE(PG8_SA(0, 0), cA, voffA); PG8_STAGE(PG8_SA(0, 1), cA + hstep, voffA);
;         if (wr == 1) PG8_BAR;
;         PG8_WAIT_V(2); PG8_BAR;
;         PG8_STAGE(PG8_SB(1, 0), cB + kstep, voffB); PG8_STAGE(PG8_SA(1, 0), cA + kstep, voffA); PG8_STAGE(PG8_SB(1, 1), cB + hstep + kstep, voffB);
;         PG8_WAIT_V(6); PG8_BAR;
;     __device__ __forceinline__ void operator()(const f32x4 (&acc)[2][2][4][2], const Unit& u, int wr, int wc, int fr, int fq) const {
;         const int cl = wc * 32 + 8 * fq, f0 = u.pn * 128 + cl;
;         PG8_LAS float* X = (PG8_LAS float*)xch;
;         f32x4 k0[2], k1[2], k2[2], kb[2];
; #pragma unroll
;         for (int n = 0; n < 2; ++n) { k0[n] = *(const f32x4*)(cw + f0 + 4 * n); k1[n] = *(const f32x4*)(cw + 2816 + f0 + 4 * n); k2[n] = *(const f32x4*)(cw + 2 * 2816 + f0 + 4 * n); kb[n] = *(const f32x4*)(cb + f0 + 4 * n); }
;         if (fr >= 14) {
; #pragma unroll
;             for (int ai = 0; ai < 2; ++ai) { PG8_LAS float* p = X + ((ai * 2 + wr) * 2 + (fr - 14)) * 128 + cl; *(PG8_LAS f32x4*)p = acc[ai][0][3][0]; *(PG8_LAS f32x4*)(p + 4) = acc[ai][0][3][1]; }
;             if (wr == 1) { float* t = TAILA + ((size_t)u.pm * 2 + (fr - 14)) * 2816 + f0; *(f32x4*)t = acc[1][0][3][0]; *(f32x4*)(t + 4) = acc[1][0][3][1]; }
;         }
;         if (wr == 0 && fr < 2) { const size_t o = ((size_t)u.pm * 2 + fr) * 2816 + f0;
;             *(f32x4*)(RAWA + o) = acc[0][0][0][0]; *(f32x4*)(RAWA + o + 4) = acc[0][0][0][1]; *(f32x4*)(RAWU + o) = acc[0][1][0][0]; *(f32x4*)(RAWU + o + 4) = acc[0][1][0][1]; }
;         asm volatile("s_waitcnt lgkmcnt(0)" ::: "memory"); __builtin_amdgcn_s_barrier(); asm volatile("" ::: "memory");
;         const int row0 = u.pm * BM + wr * 64 + fr;
; #pragma unroll
;         for (int ai = 0; ai < 2; ++ai) {
;             f32x4 P[2] = {{0.f, 0.f, 0.f, 0.f}, {0.f, 0.f, 0.f, 0.f}};
;             if (!(ai == 0 && wr == 0) && fr >= 14) { const int pai = (wr == 1) ? ai : ai - 1, pwr = (wr == 1) ? 0 : 1;
.LBB0_1731:
	s_add_u32 s14, s6, 0x6b00000
	s_addc_u32 s15, s7, 0
	s_add_u32 s16, s6, 0x200000
	s_addc_u32 s17, s7, 0
	s_add_u32 s18, s6, 0x380000
	s_addc_u32 s19, s7, 0
	s_add_u32 s20, s6, 0x500000
	s_addc_u32 s21, s7, 0
	s_waitcnt lgkmcnt(0)
	s_add_u32 s22, s8, 0x8400
	s_addc_u32 s23, s9, 0
	s_add_u32 s28, s10, 0x2c00
	s_addc_u32 s29, s11, 0
	s_lshl_b32 s6, s30, 5
	s_mov_b64 s[30:31], 0x80
	s_and_b32 s11, s6, 0x60
	s_add_i32 m0, s36, 0x18000
	v_lshl_add_u64 v[8:9], v[8:9], 0, s[30:31]
	s_lshl_b32 s10, s44, 13
	s_lshl_b32 s39, s11, 7
	global_load_lds_dwordx4 v[8:9], off
	v_lshl_add_u64 v[6:7], v[6:7], 0, s[30:31]
	s_add_i32 m0, s36, 0x1a000
	s_add_i32 s68, s36, 0x8000
	s_add_i32 s69, s36, 0xa000
	global_load_lds_dwordx4 v[6:7], off
	v_lshl_add_u64 v[2:3], v[2:3], 0, s[30:31]
	s_mov_b32 m0, s68
	s_add_u32 s6, s60, 0x40080
	global_load_lds_dwordx4 v[2:3], off
	v_lshl_add_u64 v[2:3], v[4:5], 0, s[30:31]
	s_mov_b32 m0, s69
	s_addc_u32 s7, s61, 0
	global_load_lds_dwordx4 v[2:3], off
	s_add_i32 m0, s36, 0x1c000
	v_lshl_add_u64 v[2:3], s[6:7], 0, v[176:177]
	global_load_lds_dwordx4 v[2:3], off
	v_lshl_add_u64 v[2:3], s[6:7], 0, v[172:173]
	s_add_i32 m0, s36, 0x1e000
	v_and_b32_e32 v180, 15, v12
	global_load_lds_dwordx4 v[2:3], off
	s_waitcnt vmcnt(8)
	s_barrier
	v_lshrrev_b32_e32 v2, 1, v12
	v_and_b32_e32 v2, 24, v2
	v_lshlrev_b32_e32 v3, 1, v2
	v_lshlrev_b32_e32 v4, 2, v12
	v_lshl_or_b32 v3, v180, 6, v3
	v_and_b32_e32 v4, 32, v4
	s_cmpk_lt_u32 s42, 0x100
	s_sext_i32_i16 s59, s38
	v_bitop3_b32 v194, v3, s39, v4 bitop3:0xde
	s_cselect_b64 s[38:39], -1, 0
	v_cmp_gt_u32_e32 vcc, 2, v180
	v_bitop3_b32 v5, v3, s10, v4 bitop3:0xde
	s_lshl_b32 s10, s44, 10
	s_and_b64 s[40:41], s[38:39], vcc
	s_cmpk_gt_u32 s42, 0xff
	v_or_b32_e32 v195, s11, v2
	v_cmp_lt_u32_e64 s[6:7], 13, v180
	v_lshl_add_u32 v2, v180, 9, s10
	s_cselect_b64 s[10:11], -1, 0
	s_and_b64 s[42:43], s[6:7], s[10:11]
	s_cmp_lg_u32 s44, 1
	s_cselect_b64 s[10:11], -1, 0
	v_cndmask_b32_e64 v3, 0, -1, s[10:11]
	s_and_b64 s[10:11], s[10:11], exec
	v_lshlrev_b32_e32 v8, 14, v15
	s_cselect_b32 s10, 2, 0
	v_and_b32_e32 v8, 0xffff8000, v8
	v_lshl_or_b32 v181, s44, 6, v180
	v_add_u32_e32 v4, s10, v180
	s_cselect_b32 s10, 0, 0x800
	s_add_u32 s44, s8, 0xb000
	v_lshl_add_u32 v8, v14, 11, v8
	v_and_b32_e32 v9, 1, v15
	s_addc_u32 s45, s9, 0
	v_lshl_or_b32 v8, v9, 6, v8
	s_add_u32 s46, s8, 0xdc00
	v_lshl_add_u32 v184, v16, 1, v8
	v_lshlrev_b32_e32 v8, 14, v10
	v_mov_b32_e32 v6, 0xffffe400
	s_addc_u32 s47, s9, 0
	s_add_i32 s8, 0, 0x20000
	v_and_b32_e32 v8, 0xffff8000, v8
	s_waitcnt vmcnt(6)
	v_lshl_add_u32 v4, v4, 9, v6
	v_lshl_add_u32 v6, v195, 2, s8
	v_lshl_add_u32 v8, v11, 11, v8
	v_and_b32_e32 v9, 1, v10
	v_add_u32_e32 v2, 0xffffe400, v2
	v_lshl_add_u32 v3, v3, 11, v6
	v_add_u32_e32 v7, s10, v6
	v_lshl_or_b32 v8, v9, 6, v8
	s_add_i32 s70, 0, 0x10000
	s_add_i32 s71, 0, 0x14000
	v_add_u32_e32 v182, -14, v180
	v_mov_b32_e32 v183, v177
	v_mov_b32_e32 v185, v177
	v_lshl_add_u32 v186, v13, 1, v8
	v_mov_b32_e32 v187, v177
	v_mov_b64_e32 v[188:189], 0x580
	v_mov_b64_e32 v[190:191], 0x57f
	v_add_u32_e32 v196, s70, v194
	v_add_u32_e32 v197, s71, v194
	v_add_u32_e32 v198, 0, v5
	v_add_u32_e32 v199, v6, v2
	s_movk_i32 s72, 0x2c00
	s_movk_i32 s73, 0xb00
	v_add_u32_e32 v200, v3, v4
	s_mov_b32 s48, 0xbfb8aa3b
	s_movk_i32 s74, 0x1600
	v_add_u32_e32 v201, v7, v4
	v_mov_b32_e32 v202, 0xb00
	s_barrier
	s_branch .LBB0_1734

; #define PG8_STAGE(bufoff, gbase, voff) do { _Pragma("unroll") for (int _i = 0; _i < 2; ++_i) \
;         __builtin_amdgcn_global_load_lds((const unsigned*)((const char*)(gbase) + (voff)[_i]), (PG8_LAS unsigned*)(lds + (bufoff) + ldsw + _i * 8192), 16, 0, 0); } while (0)
; #define PG8_WAIT_V(n) asm volatile("s_waitcnt vmcnt(" #n ")" ::: "memory")
; #define PG8_BAR __builtin_amdgcn_s_barrier()
; template <class Epi, class Sched, bool ALIGN_EPI = false, bool SP2 = false, bool PAIR_ACC = false>
; __device__ __forceinline__ void gemm_phase(PG8_LAS unsigned char* lds, const Gemm g, const Sched& S, const Epi& E) {
;     ...
;     f32x4 acc[2][2][4][2];
; #pragma unroll
;     for (int a = 0; a < 2; ++a)
; #pragma unroll
;         for (int b = 0; b < 2; ++b)
; #pragma unroll
;             for (int m = 0; m < 4; ++m)
; #pragma unroll
;                 for (int n = 0; n < 2; ++n) acc[a][b][m][n] = (f32x4){0.f, 0.f, 0.f, 0.f};
;     ...
;         PG8_STAGE(PG8_SB(0, 0), cB, voffB); PG8_STAGE(PG8_SB(0, 1), cB + hstep, voffB); PG8_STAGE(PG8_SA(0, 0), cA, voffA); PG8_STAGE(PG8_SA(0, 1), cA + hstep, voffA);
;         if (wr == 1) PG8_BAR;
;         PG8_WAIT_V(2); PG8_BAR;
;         PG8_STAGE(PG8_SB(1, 0), cB + kstep, voffB); PG8_STAGE(PG8_SA(1, 0), cA + kstep, voffA); PG8_STAGE(PG8_SB(1, 1), cB + hstep + kstep, voffB);
;         PG8_WAIT_V(6); PG8_BAR;
.LBB0_1826:
	v_and_b32_e32 v167, 15, v0
	s_waitcnt vmcnt(0)
	v_and_b32_e32 v18, 48, v0
	v_lshlrev_b32_e32 v19, 2, v0
	s_mov_b64 s[20:21], 0x80
	s_and_b32 s34, s15, 3
	s_lshl_b32 s0, s33, 13
	v_lshl_or_b32 v18, v167, 6, v18
	v_and_b32_e32 v19, 32, v19
	s_add_i32 m0, s38, 0x18000
	v_lshl_add_u64 v[8:9], v[8:9], 0, s[20:21]
	v_bitop3_b32 v20, v18, s0, v19 bitop3:0xde
	s_lshl_b32 s0, s34, 12
	global_load_lds_dwordx4 v[8:9], off
	v_lshl_add_u64 v[6:7], v[6:7], 0, s[20:21]
	s_add_i32 m0, s38, 0x1a000
	s_add_i32 s43, s38, 0x8000
	s_add_i32 s44, s38, 0xa000
	global_load_lds_dwordx4 v[6:7], off
	v_lshl_add_u64 v[4:5], v[4:5], 0, s[20:21]
	s_mov_b32 m0, s43
	s_add_u32 s6, s24, 0xb0080
	global_load_lds_dwordx4 v[4:5], off
	v_lshl_add_u64 v[2:3], v[2:3], 0, s[20:21]
	s_mov_b32 m0, s44
	s_addc_u32 s7, s25, 0
	global_load_lds_dwordx4 v[2:3], off
	s_add_i32 m0, s38, 0x1c000
	v_lshl_add_u64 v[2:3], s[6:7], 0, v[132:133]
	global_load_lds_dwordx4 v[2:3], off
	v_lshl_add_u64 v[2:3], s[6:7], 0, v[136:137]
	s_add_i32 m0, s38, 0x1e000
	s_sext_i32_i8 s14, s5
	global_load_lds_dwordx4 v[2:3], off
	s_waitcnt vmcnt(8)
	s_barrier
	v_lshrrev_b32_e32 v3, 1, v10
	v_mul_lo_u32 v2, v12, s4
	s_mov_b32 s5, 0xb000
	v_mad_u64_u32 v[2:3], s[6:7], v3, s5, v[2:3]
	v_or_b32_e32 v2, v2, v11
	v_bitop3_b32 v150, v18, s0, v19 bitop3:0xde
	s_mov_b64 s[0:1], 0xb0080
	v_add_lshl_u32 v2, v2, v13, 1
	v_mov_b32_e32 v3, v133
	v_lshl_add_u64 v[138:139], v[2:3], 0, s[0:1]
	v_lshrrev_b32_e32 v3, 1, v14
	v_mul_lo_u32 v2, v15, s4
	v_mad_u64_u32 v[2:3], s[4:5], v3, s5, v[2:3]
	s_waitcnt vmcnt(6)
	v_or_b32_e32 v2, v2, v16
	v_add_lshl_u32 v2, v2, v17, 1
	v_mov_b32_e32 v3, v133
	v_lshl_or_b32 v166, s33, 6, v167
	v_lshl_add_u64 v[140:141], v[2:3], 0, s[0:1]
	v_mov_b64_e32 v[142:143], 0x100
	v_mov_b64_e32 v[144:145], 0xff
	s_add_i32 s45, 0, 0x10000
	s_add_i32 s46, 0, 0x14000
	v_add_u32_e32 v151, 0, v20
	v_mov_b32_e32 v2, v133
	v_mov_b32_e32 v4, v133
	v_mov_b32_e32 v5, v133
	v_mov_b32_e32 v6, v133
	v_mov_b32_e32 v7, v133
	v_mov_b32_e32 v8, v133
	v_mov_b32_e32 v9, v133
	v_mov_b32_e32 v18, v133
	v_mov_b32_e32 v19, v133
	v_mov_b32_e32 v20, v133
	v_mov_b32_e32 v21, v133
	v_mov_b32_e32 v22, v133
	v_mov_b32_e32 v23, v133
	v_mov_b32_e32 v24, v133
	v_mov_b32_e32 v25, v133
	v_mov_b32_e32 v34, v133
	v_mov_b32_e32 v35, v133
	v_mov_b32_e32 v36, v133
	v_mov_b32_e32 v37, v133
	v_mov_b32_e32 v38, v133
	v_mov_b32_e32 v39, v133
	v_mov_b32_e32 v40, v133
	v_mov_b32_e32 v41, v133
	v_mov_b32_e32 v50, v133
	v_mov_b32_e32 v51, v133
	v_mov_b32_e32 v52, v133
	v_mov_b32_e32 v53, v133
	v_mov_b32_e32 v54, v133
	v_mov_b32_e32 v55, v133
	v_mov_b32_e32 v56, v133
	v_mov_b32_e32 v57, v133
	v_mov_b32_e32 v10, v133
	v_mov_b32_e32 v11, v133
	v_mov_b32_e32 v12, v133
	v_mov_b32_e32 v13, v133
	v_mov_b32_e32 v14, v133
	v_mov_b32_e32 v15, v133
	v_mov_b32_e32 v16, v133
	v_mov_b32_e32 v17, v133
	v_mov_b32_e32 v26, v133
	v_mov_b32_e32 v27, v133
	v_mov_b32_e32 v28, v133
	v_mov_b32_e32 v29, v133
	v_mov_b32_e32 v30, v133
	v_mov_b32_e32 v31, v133
	v_mov_b32_e32 v32, v133
	v_mov_b32_e32 v33, v133
	v_mov_b32_e32 v42, v133
	v_mov_b32_e32 v43, v133
	v_mov_b32_e32 v44, v133
	v_mov_b32_e32 v45, v133
	v_mov_b32_e32 v46, v133
	v_mov_b32_e32 v47, v133
	v_mov_b32_e32 v48, v133
	v_mov_b32_e32 v49, v133
	v_mov_b32_e32 v58, v133
	v_mov_b32_e32 v59, v133
	v_mov_b32_e32 v60, v133
	v_mov_b32_e32 v61, v133
	v_mov_b32_e32 v62, v133
	v_mov_b32_e32 v63, v133
	v_mov_b32_e32 v64, v133
	v_mov_b32_e32 v65, v133
	v_mov_b32_e32 v66, v133
	v_mov_b32_e32 v67, v133
	v_mov_b32_e32 v68, v133
	v_mov_b32_e32 v69, v133
	v_mov_b32_e32 v70, v133
	v_mov_b32_e32 v71, v133
	v_mov_b32_e32 v72, v133
	v_mov_b32_e32 v73, v133
	v_mov_b32_e32 v98, v133
	v_mov_b32_e32 v99, v133
	v_mov_b32_e32 v100, v133
	v_mov_b32_e32 v101, v133
	v_mov_b32_e32 v110, v133
	v_mov_b32_e32 v111, v133
	v_mov_b32_e32 v112, v133
	v_mov_b32_e32 v113, v133
	v_mov_b32_e32 v90, v133
	v_mov_b32_e32 v91, v133
	v_mov_b32_e32 v92, v133
	v_mov_b32_e32 v93, v133
	v_mov_b32_e32 v94, v133
	v_mov_b32_e32 v95, v133
	v_mov_b32_e32 v96, v133
	v_mov_b32_e32 v97, v133
	v_mov_b32_e32 v82, v133
	v_mov_b32_e32 v83, v133
	v_mov_b32_e32 v84, v133
	v_mov_b32_e32 v85, v133
	v_mov_b32_e32 v86, v133
	v_mov_b32_e32 v87, v133
	v_mov_b32_e32 v88, v133
	v_mov_b32_e32 v89, v133
	v_mov_b32_e32 v74, v133
	v_mov_b32_e32 v75, v133
	v_mov_b32_e32 v76, v133
	v_mov_b32_e32 v77, v133
	v_mov_b32_e32 v78, v133
	v_mov_b32_e32 v79, v133
	v_mov_b32_e32 v80, v133
	v_mov_b32_e32 v81, v133
	v_mov_b32_e32 v122, v133
	v_mov_b32_e32 v123, v133
	v_mov_b32_e32 v124, v133
	v_mov_b32_e32 v125, v133
	v_mov_b32_e32 v126, v133
	v_mov_b32_e32 v127, v133
	v_mov_b32_e32 v128, v133
	v_mov_b32_e32 v129, v133
	v_mov_b32_e32 v118, v133
	v_mov_b32_e32 v119, v133
	v_mov_b32_e32 v120, v133
	v_mov_b32_e32 v121, v133
	v_mov_b32_e32 v114, v133
	v_mov_b32_e32 v115, v133
	v_mov_b32_e32 v116, v133
	v_mov_b32_e32 v117, v133
	v_mov_b32_e32 v106, v133
	v_mov_b32_e32 v107, v133
	v_mov_b32_e32 v108, v133
	v_mov_b32_e32 v109, v133
	v_mov_b32_e32 v102, v133
	v_mov_b32_e32 v103, v133
	v_mov_b32_e32 v104, v133
	v_mov_b32_e32 v105, v133
	s_barrier
	s_branch .LBB0_1829
